# v37: residual epilogue issues the next row-group loads as soon as their staging registers free up (before the stores of the current group)
# speedup vs baseline: 1.0026x; 1.0026x over previous
;   __device__ __forceinline__ void operator()(const f32x4 (&acc)[2][2][4][2], const Unit& u, int wr, int wc, int fr, int fq) const {
;     const int mr = (u.pm * 256 < ML) ? ((u.pm * 256) >> 11) : 32;
;     const float* gp = mod + (size_t)mr * 6144 + gate_off;
; #pragma unroll
;     for (int ai = 0; ai < 2; ++ai)
; #pragma unroll
;       for (int m = 0; m < 4; ++m) {
;         const int r = u.pm * 256 + ai * 128 + wr * 64 + m * 16 + fr;
;         const float* xi = (r < ML) ? xin_l + (size_t)r * 1024 : xin_c + (size_t)(r - ML) * 1024;
;         float* xo = (r < ML) ? xout_l + (size_t)r * 1024 : xout_c + (size_t)(r - ML) * 1024;
; #pragma unroll
;         for (int bj = 0; bj < 2; ++bj)
; #pragma unroll
;           for (int n = 0; n < 2; ++n) {
;             const int c = u.pn * 256 + bj * 128 + wc * 32 + n * 16 + 4 * fq;
;             const float4 g = *reinterpret_cast<const float4*>(gp + c);
;             const float4 x = *reinterpret_cast<const float4*>(xi + c);
;             const f32x4 v = acc[ai][bj][m][n];
;             *reinterpret_cast<float4*>(xo + c) = make_float4(x.x + g.x * v[0], x.y + g.y * v[1], x.z + g.z * v[2], x.w + g.w * v[3]);
;           }
;       }
;   }
.LBB0_1478:
	s_lshl_b64 s[18:19], s[18:19], 2
	s_add_u32 s18, s46, s18
	s_addc_u32 s19, s47, s19
	v_lshl_or_b32 v140, s49, 8, v144
	v_lshlrev_b32_e32 v140, 2, v140
	global_load_dwordx4 v[146:149], v140, s[18:19]
	global_load_dwordx4 v[150:153], v140, s[18:19] offset:64
	global_load_dwordx4 v[154:157], v140, s[18:19] offset:512
	global_load_dwordx4 v[158:161], v140, s[18:19] offset:576
	s_cmpk_lt_i32 s16, 0x100
	s_cselect_b32 s100, s41, s43
	s_cselect_b32 s101, s40, s42
	s_cselect_b32 s24, s74, s62
	s_cselect_b32 s25, s75, s63
	s_cselect_b32 s1, 0, 0x100
	s_sub_i32 s1, s16, s1
	s_lshl_b32 s1, s1, 20
	v_lshlrev_b32_e32 v141, 12, v1
	v_add3_u32 v141, v141, v140, s1
	v_add_u32_e32 v142, 0x10000, v141
	global_load_dwordx4 v[204:207], v142, s[100:101]
	global_load_dwordx4 v[208:211], v142, s[100:101] offset:64
	global_load_dwordx4 v[212:215], v142, s[100:101] offset:512
	global_load_dwordx4 v[216:219], v142, s[100:101] offset:576
	v_add_u32_e32 v143, 0x20000, v141
	global_load_dwordx4 v[220:223], v143, s[100:101]
	global_load_dwordx4 v[224:227], v143, s[100:101] offset:64
	global_load_dwordx4 v[228:231], v143, s[100:101] offset:512
	global_load_dwordx4 v[182:185], v143, s[100:101] offset:576
	v_add_u32_e32 v174, 0x30000, v141
	global_load_dwordx4 v[162:165], v174, s[100:101]
	global_load_dwordx4 v[166:169], v174, s[100:101] offset:64
	global_load_dwordx4 v[170:173], v174, s[100:101] offset:512
	global_load_dwordx4 v[200:203], v174, s[100:101] offset:576
	s_mov_b32 s49, s0
	s_mov_b32 s16, s10
	s_mov_b64 s[20:21], s[14:15]
	s_mov_b64 s[18:19], s[12:13]
	s_and_b64 vcc, exec, s[6:7]
	s_waitcnt vmcnt(12)
	v_pk_fma_f32 v[126:127], v[126:127], v[146:147], v[234:235]
	v_pk_fma_f32 v[128:129], v[128:129], v[148:149], v[236:237]
	v_pk_fma_f32 v[122:123], v[122:123], v[150:151], v[238:239]
	v_pk_fma_f32 v[124:125], v[124:125], v[152:153], v[240:241]
	v_pk_fma_f32 v[118:119], v[118:119], v[154:155], v[242:243]
	v_pk_fma_f32 v[120:121], v[120:121], v[156:157], v[244:245]
	v_pk_fma_f32 v[114:115], v[114:115], v[158:159], v[246:247]
	v_pk_fma_f32 v[116:117], v[116:117], v[160:161], v[248:249]
	v_add_u32_e32 v175, 0x80000, v141
	global_load_dwordx4 v[234:237], v175, s[100:101]
	global_load_dwordx4 v[238:241], v175, s[100:101] offset:64
	global_load_dwordx4 v[242:245], v175, s[100:101] offset:512
	global_load_dwordx4 v[246:249], v175, s[100:101] offset:576
	global_store_dwordx4 v141, v[126:129], s[24:25]
	global_store_dwordx4 v141, v[122:125], s[24:25] offset:64
	global_store_dwordx4 v141, v[118:121], s[24:25] offset:512
	global_store_dwordx4 v141, v[114:117], s[24:25] offset:576
	v_add_u32_e32 v232, 0x90000, v141
	global_load_dwordx4 v[126:129], v232, s[100:101]
	global_load_dwordx4 v[122:125], v232, s[100:101] offset:64
	global_load_dwordx4 v[118:121], v232, s[100:101] offset:512
	global_load_dwordx4 v[114:117], v232, s[100:101] offset:576
	s_waitcnt vmcnt(20)
	v_pk_fma_f32 v[110:111], v[110:111], v[146:147], v[204:205]
	v_pk_fma_f32 v[112:113], v[112:113], v[148:149], v[206:207]
	v_pk_fma_f32 v[106:107], v[106:107], v[150:151], v[208:209]
	v_pk_fma_f32 v[108:109], v[108:109], v[152:153], v[210:211]
	v_pk_fma_f32 v[102:103], v[102:103], v[154:155], v[212:213]
	v_pk_fma_f32 v[104:105], v[104:105], v[156:157], v[214:215]
	v_pk_fma_f32 v[98:99], v[98:99], v[158:159], v[216:217]
	v_pk_fma_f32 v[100:101], v[100:101], v[160:161], v[218:219]
	v_add_u32_e32 v233, 0xa0000, v141
	global_load_dwordx4 v[204:207], v233, s[100:101]
	global_load_dwordx4 v[208:211], v233, s[100:101] offset:64
	global_load_dwordx4 v[212:215], v233, s[100:101] offset:512
	global_load_dwordx4 v[216:219], v233, s[100:101] offset:576
	global_store_dwordx4 v142, v[110:113], s[24:25]
	global_store_dwordx4 v142, v[106:109], s[24:25] offset:64
	global_store_dwordx4 v142, v[102:105], s[24:25] offset:512
	global_store_dwordx4 v142, v[98:101], s[24:25] offset:576
	v_add_u32_e32 v142, 0xb0000, v141
	global_load_dwordx4 v[110:113], v142, s[100:101]
	global_load_dwordx4 v[106:109], v142, s[100:101] offset:64
	global_load_dwordx4 v[102:105], v142, s[100:101] offset:512
	global_load_dwordx4 v[98:101], v142, s[100:101] offset:576
	s_waitcnt vmcnt(28)
;   __device__ __forceinline__ void operator()(const f32x4 (&acc)[2][2][4][2], const Unit& u, int wr, int wc, int fr, int fq) const {
;     const int mr = (u.pm * 256 < ML) ? ((u.pm * 256) >> 11) : 32;
;     const float* gp = mod + (size_t)mr * 6144 + gate_off;
; #pragma unroll
;     for (int ai = 0; ai < 2; ++ai)
; #pragma unroll
;       for (int m = 0; m < 4; ++m) {
;         const int r = u.pm * 256 + ai * 128 + wr * 64 + m * 16 + fr;
;         const float* xi = (r < ML) ? xin_l + (size_t)r * 1024 : xin_c + (size_t)(r - ML) * 1024;
;         float* xo = (r < ML) ? xout_l + (size_t)r * 1024 : xout_c + (size_t)(r - ML) * 1024;
; #pragma unroll
;         for (int bj = 0; bj < 2; ++bj)
; #pragma unroll
;           for (int n = 0; n < 2; ++n) {
;             const int c = u.pn * 256 + bj * 128 + wc * 32 + n * 16 + 4 * fq;
;             const float4 g = *reinterpret_cast<const float4*>(gp + c);
;             const float4 x = *reinterpret_cast<const float4*>(xi + c);
;             const f32x4 v = acc[ai][bj][m][n];
;             *reinterpret_cast<float4*>(xo + c) = make_float4(x.x + g.x * v[0], x.y + g.y * v[1], x.z + g.z * v[2], x.w + g.w * v[3]);
;           }
;       }
;   }
	v_pk_fma_f32 v[94:95], v[94:95], v[146:147], v[220:221]
	v_pk_fma_f32 v[96:97], v[96:97], v[148:149], v[222:223]
	v_pk_fma_f32 v[90:91], v[90:91], v[150:151], v[224:225]
	v_pk_fma_f32 v[92:93], v[92:93], v[152:153], v[226:227]
	v_pk_fma_f32 v[86:87], v[86:87], v[154:155], v[228:229]
	v_pk_fma_f32 v[88:89], v[88:89], v[156:157], v[230:231]
	v_pk_fma_f32 v[82:83], v[82:83], v[158:159], v[182:183]
	v_pk_fma_f32 v[84:85], v[84:85], v[160:161], v[184:185]
	global_store_dwordx4 v143, v[94:97], s[24:25]
	global_store_dwordx4 v143, v[90:93], s[24:25] offset:64
	global_store_dwordx4 v143, v[86:89], s[24:25] offset:512
	global_store_dwordx4 v143, v[82:85], s[24:25] offset:576
	s_waitcnt vmcnt(28)
	v_pk_fma_f32 v[78:79], v[78:79], v[146:147], v[162:163]
	v_pk_fma_f32 v[80:81], v[80:81], v[148:149], v[164:165]
	v_pk_fma_f32 v[74:75], v[74:75], v[150:151], v[166:167]
	v_pk_fma_f32 v[76:77], v[76:77], v[152:153], v[168:169]
	v_pk_fma_f32 v[70:71], v[70:71], v[154:155], v[170:171]
	v_pk_fma_f32 v[72:73], v[72:73], v[156:157], v[172:173]
	v_pk_fma_f32 v[66:67], v[66:67], v[158:159], v[200:201]
	v_pk_fma_f32 v[68:69], v[68:69], v[160:161], v[202:203]
	global_store_dwordx4 v174, v[78:81], s[24:25]
	global_store_dwordx4 v174, v[74:77], s[24:25] offset:64
	global_store_dwordx4 v174, v[70:73], s[24:25] offset:512
	global_store_dwordx4 v174, v[66:69], s[24:25] offset:576
	s_waitcnt vmcnt(28)
	v_pk_fma_f32 v[62:63], v[62:63], v[146:147], v[234:235]
	v_pk_fma_f32 v[64:65], v[64:65], v[148:149], v[236:237]
	v_pk_fma_f32 v[58:59], v[58:59], v[150:151], v[238:239]
	v_pk_fma_f32 v[60:61], v[60:61], v[152:153], v[240:241]
	v_pk_fma_f32 v[54:55], v[54:55], v[154:155], v[242:243]
	v_pk_fma_f32 v[56:57], v[56:57], v[156:157], v[244:245]
	v_pk_fma_f32 v[50:51], v[50:51], v[158:159], v[246:247]
	v_pk_fma_f32 v[52:53], v[52:53], v[160:161], v[248:249]
	global_store_dwordx4 v175, v[62:65], s[24:25]
	global_store_dwordx4 v175, v[58:61], s[24:25] offset:64
	global_store_dwordx4 v175, v[54:57], s[24:25] offset:512
	global_store_dwordx4 v175, v[50:53], s[24:25] offset:576
	s_waitcnt vmcnt(24)
	v_pk_fma_f32 v[46:47], v[46:47], v[146:147], v[126:127]
	v_pk_fma_f32 v[48:49], v[48:49], v[148:149], v[128:129]
	v_pk_fma_f32 v[42:43], v[42:43], v[150:151], v[122:123]
	v_pk_fma_f32 v[44:45], v[44:45], v[152:153], v[124:125]
	v_pk_fma_f32 v[38:39], v[38:39], v[154:155], v[118:119]
	v_pk_fma_f32 v[40:41], v[40:41], v[156:157], v[120:121]
	v_pk_fma_f32 v[34:35], v[34:35], v[158:159], v[114:115]
	v_pk_fma_f32 v[36:37], v[36:37], v[160:161], v[116:117]
	global_store_dwordx4 v232, v[46:49], s[24:25]
	global_store_dwordx4 v232, v[42:45], s[24:25] offset:64
	global_store_dwordx4 v232, v[38:41], s[24:25] offset:512
	global_store_dwordx4 v232, v[34:37], s[24:25] offset:576
	s_waitcnt vmcnt(24)
	v_pk_fma_f32 v[30:31], v[30:31], v[146:147], v[204:205]
	v_pk_fma_f32 v[32:33], v[32:33], v[148:149], v[206:207]
	v_pk_fma_f32 v[26:27], v[26:27], v[150:151], v[208:209]
	v_pk_fma_f32 v[28:29], v[28:29], v[152:153], v[210:211]
	v_pk_fma_f32 v[22:23], v[22:23], v[154:155], v[212:213]
	v_pk_fma_f32 v[24:25], v[24:25], v[156:157], v[214:215]
	v_pk_fma_f32 v[18:19], v[18:19], v[158:159], v[216:217]
	v_pk_fma_f32 v[20:21], v[20:21], v[160:161], v[218:219]
	global_store_dwordx4 v233, v[30:33], s[24:25]
	global_store_dwordx4 v233, v[26:29], s[24:25] offset:64
	global_store_dwordx4 v233, v[22:25], s[24:25] offset:512
	global_store_dwordx4 v233, v[18:21], s[24:25] offset:576
	s_waitcnt vmcnt(20)
	v_pk_fma_f32 v[14:15], v[14:15], v[146:147], v[110:111]
	v_pk_fma_f32 v[16:17], v[16:17], v[148:149], v[112:113]
	v_pk_fma_f32 v[10:11], v[10:11], v[150:151], v[106:107]
	v_pk_fma_f32 v[12:13], v[12:13], v[152:153], v[108:109]
	v_pk_fma_f32 v[6:7], v[6:7], v[154:155], v[102:103]
	v_pk_fma_f32 v[8:9], v[8:9], v[156:157], v[104:105]
	v_pk_fma_f32 v[2:3], v[2:3], v[158:159], v[98:99]
	v_pk_fma_f32 v[4:5], v[4:5], v[160:161], v[100:101]
	global_store_dwordx4 v142, v[14:17], s[24:25]
	global_store_dwordx4 v142, v[10:13], s[24:25] offset:64
	global_store_dwordx4 v142, v[6:9], s[24:25] offset:512
	global_store_dwordx4 v142, v[2:5], s[24:25] offset:576
	s_cbranch_vccnz .LBB0_1485

;   __device__ __forceinline__ void operator()(const f32x4 (&acc)[2][2][4][2], const Unit& u, int wr, int wc, int fr, int fq) const {
;     const int mr = (u.pm * 256 < ML) ? ((u.pm * 256) >> 11) : 32;
;     const float* gp = mod + (size_t)mr * 6144 + gate_off;
; #pragma unroll
;     for (int ai = 0; ai < 2; ++ai)
; #pragma unroll
;       for (int m = 0; m < 4; ++m) {
;         const int r = u.pm * 256 + ai * 128 + wr * 64 + m * 16 + fr;
;         const float* xi = (r < ML) ? xin_l + (size_t)r * 1024 : xin_c + (size_t)(r - ML) * 1024;
;         float* xo = (r < ML) ? xout_l + (size_t)r * 1024 : xout_c + (size_t)(r - ML) * 1024;
; #pragma unroll
;         for (int bj = 0; bj < 2; ++bj)
; #pragma unroll
;           for (int n = 0; n < 2; ++n) {
;             const int c = u.pn * 256 + bj * 128 + wc * 32 + n * 16 + 4 * fq;
;             const float4 g = *reinterpret_cast<const float4*>(gp + c);
;             const float4 x = *reinterpret_cast<const float4*>(xi + c);
;             const f32x4 v = acc[ai][bj][m][n];
;             *reinterpret_cast<float4*>(xo + c) = make_float4(x.x + g.x * v[0], x.y + g.y * v[1], x.z + g.z * v[2], x.w + g.w * v[3]);
;           }
;       }
;   }
.LBB0_1665:
	s_lshl_b64 s[10:11], s[10:11], 2
	s_add_u32 s10, s30, s10
	s_addc_u32 s11, s31, s11
	v_lshl_or_b32 v140, s38, 8, v144
	v_lshlrev_b32_e32 v140, 2, v140
	global_load_dwordx4 v[146:149], v140, s[10:11]
	global_load_dwordx4 v[150:153], v140, s[10:11] offset:64
	global_load_dwordx4 v[154:157], v140, s[10:11] offset:512
	global_load_dwordx4 v[158:161], v140, s[10:11] offset:576
	s_cmpk_lt_i32 s37, 0x100
	s_cselect_b64 s[100:101], s[74:75], s[62:63]
	s_cselect_b32 s10, 0, 0x100
	s_sub_i32 s10, s37, s10
	s_lshl_b32 s10, s10, 20
	v_lshlrev_b32_e32 v141, 12, v1
	v_add3_u32 v141, v141, v140, s10
	v_add_u32_e32 v142, 0x10000, v141
	global_load_dwordx4 v[204:207], v142, s[100:101]
	global_load_dwordx4 v[208:211], v142, s[100:101] offset:64
	global_load_dwordx4 v[212:215], v142, s[100:101] offset:512
	global_load_dwordx4 v[216:219], v142, s[100:101] offset:576
	v_add_u32_e32 v143, 0x20000, v141
	global_load_dwordx4 v[220:223], v143, s[100:101]
	global_load_dwordx4 v[224:227], v143, s[100:101] offset:64
	global_load_dwordx4 v[228:231], v143, s[100:101] offset:512
	global_load_dwordx4 v[182:185], v143, s[100:101] offset:576
	v_add_u32_e32 v174, 0x30000, v141
	global_load_dwordx4 v[162:165], v174, s[100:101]
	global_load_dwordx4 v[166:169], v174, s[100:101] offset:64
	global_load_dwordx4 v[170:173], v174, s[100:101] offset:512
	global_load_dwordx4 v[200:203], v174, s[100:101] offset:576
	v_readlane_b32 s40, v253, 12
	v_readlane_b32 s41, v253, 13
	v_readlane_b32 s44, v253, 16
	v_readlane_b32 s45, v253, 17
	v_readlane_b32 s52, v253, 24
	v_readlane_b32 s53, v253, 25
	v_readlane_b32 s54, v253, 26
	v_readlane_b32 s55, v253, 27
	v_readlane_b32 s42, v253, 14
	v_readlane_b32 s43, v253, 15
	v_readlane_b32 s46, v253, 18
	v_readlane_b32 s47, v253, 19
	v_readlane_b32 s48, v253, 20
	v_readlane_b32 s49, v253, 21
	v_readlane_b32 s50, v253, 22
	v_readlane_b32 s51, v253, 23
	s_mov_b32 s38, s35
	s_mov_b32 s37, s36
	s_mov_b64 s[12:13], s[0:1]
	s_and_b64 vcc, exec, s[4:5]
	s_waitcnt vmcnt(12)
	v_pk_fma_f32 v[126:127], v[126:127], v[146:147], v[234:235]
	v_pk_fma_f32 v[128:129], v[128:129], v[148:149], v[236:237]
	v_pk_fma_f32 v[122:123], v[122:123], v[150:151], v[238:239]
	v_pk_fma_f32 v[124:125], v[124:125], v[152:153], v[240:241]
	v_pk_fma_f32 v[118:119], v[118:119], v[154:155], v[242:243]
	v_pk_fma_f32 v[120:121], v[120:121], v[156:157], v[244:245]
	v_pk_fma_f32 v[114:115], v[114:115], v[158:159], v[246:247]
	v_pk_fma_f32 v[116:117], v[116:117], v[160:161], v[248:249]
	v_add_u32_e32 v175, 0x80000, v141
	global_load_dwordx4 v[234:237], v175, s[100:101]
	global_load_dwordx4 v[238:241], v175, s[100:101] offset:64
	global_load_dwordx4 v[242:245], v175, s[100:101] offset:512
	global_load_dwordx4 v[246:249], v175, s[100:101] offset:576
	global_store_dwordx4 v141, v[126:129], s[100:101]
	global_store_dwordx4 v141, v[122:125], s[100:101] offset:64
	global_store_dwordx4 v141, v[118:121], s[100:101] offset:512
	global_store_dwordx4 v141, v[114:117], s[100:101] offset:576
	v_add_u32_e32 v232, 0x90000, v141
	global_load_dwordx4 v[126:129], v232, s[100:101]
	global_load_dwordx4 v[122:125], v232, s[100:101] offset:64
	global_load_dwordx4 v[118:121], v232, s[100:101] offset:512
	global_load_dwordx4 v[114:117], v232, s[100:101] offset:576
	s_waitcnt vmcnt(20)
	v_pk_fma_f32 v[110:111], v[110:111], v[146:147], v[204:205]
	v_pk_fma_f32 v[112:113], v[112:113], v[148:149], v[206:207]
	v_pk_fma_f32 v[106:107], v[106:107], v[150:151], v[208:209]
	v_pk_fma_f32 v[108:109], v[108:109], v[152:153], v[210:211]
	v_pk_fma_f32 v[102:103], v[102:103], v[154:155], v[212:213]
	v_pk_fma_f32 v[104:105], v[104:105], v[156:157], v[214:215]
	v_pk_fma_f32 v[98:99], v[98:99], v[158:159], v[216:217]
	v_pk_fma_f32 v[100:101], v[100:101], v[160:161], v[218:219]
	v_add_u32_e32 v233, 0xa0000, v141
	global_load_dwordx4 v[204:207], v233, s[100:101]
	global_load_dwordx4 v[208:211], v233, s[100:101] offset:64
	global_load_dwordx4 v[212:215], v233, s[100:101] offset:512
	global_load_dwordx4 v[216:219], v233, s[100:101] offset:576
	global_store_dwordx4 v142, v[110:113], s[100:101]
	global_store_dwordx4 v142, v[106:109], s[100:101] offset:64
	global_store_dwordx4 v142, v[102:105], s[100:101] offset:512
	global_store_dwordx4 v142, v[98:101], s[100:101] offset:576
	v_add_u32_e32 v142, 0xb0000, v141
	global_load_dwordx4 v[110:113], v142, s[100:101]
	global_load_dwordx4 v[106:109], v142, s[100:101] offset:64
	global_load_dwordx4 v[102:105], v142, s[100:101] offset:512
	global_load_dwordx4 v[98:101], v142, s[100:101] offset:576
	s_waitcnt vmcnt(28)
;   __device__ __forceinline__ void operator()(const f32x4 (&acc)[2][2][4][2], const Unit& u, int wr, int wc, int fr, int fq) const {
;     const int mr = (u.pm * 256 < ML) ? ((u.pm * 256) >> 11) : 32;
;     const float* gp = mod + (size_t)mr * 6144 + gate_off;
; #pragma unroll
;     for (int ai = 0; ai < 2; ++ai)
; #pragma unroll
;       for (int m = 0; m < 4; ++m) {
;         const int r = u.pm * 256 + ai * 128 + wr * 64 + m * 16 + fr;
;         const float* xi = (r < ML) ? xin_l + (size_t)r * 1024 : xin_c + (size_t)(r - ML) * 1024;
;         float* xo = (r < ML) ? xout_l + (size_t)r * 1024 : xout_c + (size_t)(r - ML) * 1024;
; #pragma unroll
;         for (int bj = 0; bj < 2; ++bj)
; #pragma unroll
;           for (int n = 0; n < 2; ++n) {
;             const int c = u.pn * 256 + bj * 128 + wc * 32 + n * 16 + 4 * fq;
;             const float4 g = *reinterpret_cast<const float4*>(gp + c);
;             const float4 x = *reinterpret_cast<const float4*>(xi + c);
;             const f32x4 v = acc[ai][bj][m][n];
;             *reinterpret_cast<float4*>(xo + c) = make_float4(x.x + g.x * v[0], x.y + g.y * v[1], x.z + g.z * v[2], x.w + g.w * v[3]);
;           }
;       }
;   }
	v_pk_fma_f32 v[94:95], v[94:95], v[146:147], v[220:221]
	v_pk_fma_f32 v[96:97], v[96:97], v[148:149], v[222:223]
	v_pk_fma_f32 v[90:91], v[90:91], v[150:151], v[224:225]
	v_pk_fma_f32 v[92:93], v[92:93], v[152:153], v[226:227]
	v_pk_fma_f32 v[86:87], v[86:87], v[154:155], v[228:229]
	v_pk_fma_f32 v[88:89], v[88:89], v[156:157], v[230:231]
	v_pk_fma_f32 v[82:83], v[82:83], v[158:159], v[182:183]
	v_pk_fma_f32 v[84:85], v[84:85], v[160:161], v[184:185]
	global_store_dwordx4 v143, v[94:97], s[100:101]
	global_store_dwordx4 v143, v[90:93], s[100:101] offset:64
	global_store_dwordx4 v143, v[86:89], s[100:101] offset:512
	global_store_dwordx4 v143, v[82:85], s[100:101] offset:576
	s_waitcnt vmcnt(28)
	v_pk_fma_f32 v[78:79], v[78:79], v[146:147], v[162:163]
	v_pk_fma_f32 v[80:81], v[80:81], v[148:149], v[164:165]
	v_pk_fma_f32 v[74:75], v[74:75], v[150:151], v[166:167]
	v_pk_fma_f32 v[76:77], v[76:77], v[152:153], v[168:169]
	v_pk_fma_f32 v[70:71], v[70:71], v[154:155], v[170:171]
	v_pk_fma_f32 v[72:73], v[72:73], v[156:157], v[172:173]
	v_pk_fma_f32 v[66:67], v[66:67], v[158:159], v[200:201]
	v_pk_fma_f32 v[68:69], v[68:69], v[160:161], v[202:203]
	global_store_dwordx4 v174, v[78:81], s[100:101]
	global_store_dwordx4 v174, v[74:77], s[100:101] offset:64
	global_store_dwordx4 v174, v[70:73], s[100:101] offset:512
	global_store_dwordx4 v174, v[66:69], s[100:101] offset:576
	s_waitcnt vmcnt(28)
	v_pk_fma_f32 v[62:63], v[62:63], v[146:147], v[234:235]
	v_pk_fma_f32 v[64:65], v[64:65], v[148:149], v[236:237]
	v_pk_fma_f32 v[58:59], v[58:59], v[150:151], v[238:239]
	v_pk_fma_f32 v[60:61], v[60:61], v[152:153], v[240:241]
	v_pk_fma_f32 v[54:55], v[54:55], v[154:155], v[242:243]
	v_pk_fma_f32 v[56:57], v[56:57], v[156:157], v[244:245]
	v_pk_fma_f32 v[50:51], v[50:51], v[158:159], v[246:247]
	v_pk_fma_f32 v[52:53], v[52:53], v[160:161], v[248:249]
	global_store_dwordx4 v175, v[62:65], s[100:101]
	global_store_dwordx4 v175, v[58:61], s[100:101] offset:64
	global_store_dwordx4 v175, v[54:57], s[100:101] offset:512
	global_store_dwordx4 v175, v[50:53], s[100:101] offset:576
	s_waitcnt vmcnt(24)
	v_pk_fma_f32 v[46:47], v[46:47], v[146:147], v[126:127]
	v_pk_fma_f32 v[48:49], v[48:49], v[148:149], v[128:129]
	v_pk_fma_f32 v[42:43], v[42:43], v[150:151], v[122:123]
	v_pk_fma_f32 v[44:45], v[44:45], v[152:153], v[124:125]
	v_pk_fma_f32 v[38:39], v[38:39], v[154:155], v[118:119]
	v_pk_fma_f32 v[40:41], v[40:41], v[156:157], v[120:121]
	v_pk_fma_f32 v[34:35], v[34:35], v[158:159], v[114:115]
	v_pk_fma_f32 v[36:37], v[36:37], v[160:161], v[116:117]
	global_store_dwordx4 v232, v[46:49], s[100:101]
	global_store_dwordx4 v232, v[42:45], s[100:101] offset:64
	global_store_dwordx4 v232, v[38:41], s[100:101] offset:512
	global_store_dwordx4 v232, v[34:37], s[100:101] offset:576
	s_waitcnt vmcnt(24)
	v_pk_fma_f32 v[30:31], v[30:31], v[146:147], v[204:205]
	v_pk_fma_f32 v[32:33], v[32:33], v[148:149], v[206:207]
	v_pk_fma_f32 v[26:27], v[26:27], v[150:151], v[208:209]
	v_pk_fma_f32 v[28:29], v[28:29], v[152:153], v[210:211]
	v_pk_fma_f32 v[22:23], v[22:23], v[154:155], v[212:213]
	v_pk_fma_f32 v[24:25], v[24:25], v[156:157], v[214:215]
	v_pk_fma_f32 v[18:19], v[18:19], v[158:159], v[216:217]
	v_pk_fma_f32 v[20:21], v[20:21], v[160:161], v[218:219]
	global_store_dwordx4 v233, v[30:33], s[100:101]
	global_store_dwordx4 v233, v[26:29], s[100:101] offset:64
	global_store_dwordx4 v233, v[22:25], s[100:101] offset:512
	global_store_dwordx4 v233, v[18:21], s[100:101] offset:576
	s_waitcnt vmcnt(20)
	v_pk_fma_f32 v[14:15], v[14:15], v[146:147], v[110:111]
	v_pk_fma_f32 v[16:17], v[16:17], v[148:149], v[112:113]
	v_pk_fma_f32 v[10:11], v[10:11], v[150:151], v[106:107]
	v_pk_fma_f32 v[12:13], v[12:13], v[152:153], v[108:109]
	v_pk_fma_f32 v[6:7], v[6:7], v[154:155], v[102:103]
	v_pk_fma_f32 v[8:9], v[8:9], v[156:157], v[104:105]
	v_pk_fma_f32 v[2:3], v[2:3], v[158:159], v[98:99]
	v_pk_fma_f32 v[4:5], v[4:5], v[160:161], v[100:101]
	global_store_dwordx4 v142, v[14:17], s[100:101]
	global_store_dwordx4 v142, v[10:13], s[100:101] offset:64
	global_store_dwordx4 v142, v[6:9], s[100:101] offset:512
	global_store_dwordx4 v142, v[2:5], s[100:101] offset:576
	s_mov_b64 s[10:11], s[6:7]
	s_cbranch_vccnz .LBB0_1676
